# baseline (speedup 1.0000x reference)
; __device__ __forceinline__ unsigned pk2(float lo, float hi) { const f32x2_t v = {lo, hi}; return __builtin_bit_cast(unsigned, __builtin_convertvector(v, bf16x2_t)); }
; __device__ __forceinline__ float lane_xor(float v, int lane, int o) { return __int_as_float(__builtin_amdgcn_ds_bpermute((lane ^ o) << 2, __float_as_int(v))); }
; __device__ __forceinline__ float wave_sum(float v, int lane) {
; #pragma unroll
;     for (int o = 1; o < 64; o <<= 1) v += lane_xor(v, lane, o);
;     return v;
;     ...
;     for (int row = r_beg; row < r_end; row += NGW) {
;         const bool isc = row >= ML; const int mod = isc ? 4 : (row >> 13);
;         f32x4 v[4];
; #pragma unroll
;         for (int j = 0; j < 4; ++j) v[j] = vn[j];
;         if (row + NGW < r_end) { const int rn = row + NGW;
; #pragma unroll
;             for (int j = 0; j < 4; ++j) vn[j] = ld_row4(srcL, xb_in, srcC, rn, lane + 64 * j); }
;         if (xb_out && !isc) {
; #pragma unroll
;             for (int j = 0; j < 4; ++j) { u32x2 w; w.x = pk2(v[j].x, v[j].y); w.y = pk2(v[j].z, v[j].w); ((u32x2*)(xb_out + (size_t)row * DM))[lane + 64 * j] = w; } }
;         if (mod != cur_mod) { cur_mod = mod; const float* shp = mods_l + mod * 6144 + sh_off; const float* scp = mods_l + mod * 6144 + sc_off;
; #pragma unroll
;             for (int j = 0; j < 4; ++j) { gs[j] = ((const f32x4*)gam)[lane + 64 * j] * (((const f32x4*)scp)[lane + 64 * j] + 1.0f); shv[j] = ((const f32x4*)shp)[lane + 64 * j]; } }
;         if (isc && npart > 0) {
;             for (int ks = 0; ks < npart; ++ks) { const f32x4* pp = (const f32x4*)(part + ((size_t)ks * MC + (row - ML)) * DM);
; #pragma unroll
;                 for (int j = 0; j < 4; ++j) v[j] += pp[lane + 64 * j]; }
; #pragma unroll
;             for (int j = 0; j < 4; ++j) ((f32x4*)(srcC + (size_t)(row - ML) * DM))[lane + 64 * j] = v[j];
;         }
;         float s = 0.f;
; #pragma unroll
;         for (int j = 0; j < 4; ++j) s += (v[j].x * v[j].x + v[j].y * v[j].y) + (v[j].z * v[j].z + v[j].w * v[j].w);
;         s = wave_sum(s, lane); const float rstd = 1.0f / sqrtf(s * (1.0f / DM) + 1e-6f);
; #pragma unroll
;         for (int j = 0; j < 4; ++j) { const f32x4 y = v[j] * rstd * gs[j] + shv[j]; u32x2 w; w.x = pk2(y.x, y.y); w.y = pk2(y.z, y.w);
;             ((u32x2*)(H + (size_t)row * DM))[lane + 64 * j] = w; }
.Ln7_modokA:
	global_load_dwordx2 v[100:101], v86, s[34:35]
	global_load_dwordx2 v[102:103], v86, s[34:35] offset:512
	global_load_dwordx2 v[104:105], v86, s[34:35] offset:1024
	global_load_dwordx2 v[106:107], v86, s[34:35] offset:1536
	s_add_i32 s11, s46, s12
	s_cmp_lt_i32 s11, 0x8000
	s_cselect_b32 s46, s11, s46
	s_cselect_b32 s11, s13, 0
	s_add_u32 s34, s34, s11
	s_addc_u32 s35, s35, 0
	v_pk_mul_f32 v[90:91], v[56:57], v[56:57]
	v_pk_mul_f32 v[92:93], v[54:55], v[54:55]
	v_pk_mul_f32 v[4:5], v[60:61], v[60:61]
	v_pk_mul_f32 v[88:89], v[58:59], v[58:59]
	v_pk_mov_b32 v[94:95], v[92:93], v[90:91] op_sel:[1,0]
	v_mov_b32_e32 v93, v91
	v_pk_add_f32 v[90:91], v[94:95], v[92:93]
	v_pk_mov_b32 v[92:93], v[88:89], v[4:5] op_sel:[1,0]
	v_mov_b32_e32 v89, v5
	v_pk_add_f32 v[4:5], v[92:93], v[88:89]
	v_pk_add_f32 v[90:91], v[90:91], v[90:91] op_sel_hi:[0,1]
	v_pk_add_f32 v[4:5], v[4:5], v[4:5] op_sel_hi:[0,1]
	v_mul_f32_e32 v4, v62, v62
	v_pk_fma_f32 v[88:89], v[62:63], v[62:63], v[4:5] op_sel_hi:[1,1,0]
	v_mul_f32_e32 v4, v64, v64
	v_pk_fma_f32 v[92:93], v[64:65], v[64:65], v[4:5] op_sel_hi:[1,1,0]
	v_mul_f32_e32 v88, v66, v66
	v_mul_f32_e32 v92, v67, v67
	v_mul_f32_e32 v90, v68, v68
	v_mul_f32_e32 v4, v69, v69
	v_pk_add_f32 v[88:89], v[88:89], v[92:93]
	v_pk_add_f32 v[4:5], v[90:91], v[4:5]
	v_pk_add_f32 v[4:5], v[88:89], v[4:5]
	s_nop 0
	v_add_f32_e32 v3, v4, v5
	s_nop 1
	v_add_f32_dpp v3, v3, v3 quad_perm:[1,0,3,2] row_mask:0xf bank_mask:0xf
	s_nop 1
	v_add_f32_dpp v3, v3, v3 quad_perm:[2,3,0,1] row_mask:0xf bank_mask:0xf
	s_nop 1
	v_add_f32_dpp v3, v3, v3 row_half_mirror row_mask:0xf bank_mask:0xf
	s_nop 1
	v_add_f32_dpp v3, v3, v3 row_mirror row_mask:0xf bank_mask:0xf
	s_nop 1
	v_readlane_b32 s4, v3, 0
	v_readlane_b32 s5, v3, 16
	v_readlane_b32 s6, v3, 32
	v_readlane_b32 s7, v3, 48
	s_nop 1
	v_mov_b32_e32 v4, s4
	v_add_f32_e32 v4, s5, v4
	v_mov_b32_e32 v5, s6
	v_add_f32_e32 v5, s7, v5
	v_add_f32_e32 v3, v4, v5
	v_fmamk_f32 v3, v3, 0x3a800000, v238
	v_mul_f32_e32 v4, 0x4f800000, v3
	v_cmp_gt_f32_e32 vcc, s58, v3
	s_nop 1
	v_cndmask_b32_e32 v3, v3, v4, vcc
	v_sqrt_f32_e32 v4, v3
	s_nop 0
	v_add_u32_e32 v5, -1, v4
	v_add_u32_e32 v75, 1, v4
	v_fma_f32 v88, -v5, v4, v3
	v_fma_f32 v89, -v75, v4, v3
	v_cmp_ge_f32_e64 s[4:5], 0, v88
	s_nop 1
	v_cndmask_b32_e64 v4, v4, v5, s[4:5]
	v_cmp_lt_f32_e64 s[4:5], 0, v89
	s_nop 1
	v_cndmask_b32_e64 v4, v4, v75, s[4:5]
	v_mul_f32_e32 v5, 0x37800000, v4
	v_cndmask_b32_e32 v4, v4, v5, vcc
	v_cmp_class_f32_e32 vcc, v3, v248
	s_nop 1
	v_cndmask_b32_e32 v3, v4, v3, vcc
	v_div_scale_f32 v75, s[4:5], v3, v3, 1.0
	v_rcp_f32_e32 v88, v75
	v_div_scale_f32 v89, vcc, 1.0, v3, 1.0
	v_fma_f32 v90, -v75, v88, 1.0
	v_fmac_f32_e32 v88, v90, v88
	v_mul_f32_e32 v90, v89, v88
	v_fma_f32 v91, -v75, v90, v89
	v_fmac_f32_e32 v90, v91, v88
	v_fma_f32 v75, -v75, v90, v89
	v_div_fmas_f32 v75, v75, v88, v90
	v_div_fixup_f32 v88, v75, v3, 1.0
	s_waitcnt vmcnt(4)
	v_pk_mul_f32 v[54:55], v[54:55], v[88:89] op_sel_hi:[1,0]
	v_pk_mul_f32 v[56:57], v[56:57], v[88:89] op_sel_hi:[1,0]
	v_pk_fma_f32 v[54:55], v[6:7], v[54:55], v[10:11]
	v_pk_fma_f32 v[56:57], v[8:9], v[56:57], v[12:13]
	v_cvt_pk_bf16_f32 v54, v54, v55
	v_cvt_pk_bf16_f32 v55, v56, v57
	global_store_dwordx2 v86, v[54:55], s[36:37]
	v_pk_mul_f32 v[54:55], v[58:59], v[88:89] op_sel_hi:[1,0]
	v_pk_mul_f32 v[56:57], v[60:61], v[88:89] op_sel_hi:[1,0]
	v_pk_fma_f32 v[54:55], v[14:15], v[54:55], v[18:19]
	v_pk_fma_f32 v[56:57], v[16:17], v[56:57], v[20:21]
	v_cvt_pk_bf16_f32 v54, v54, v55
	v_cvt_pk_bf16_f32 v55, v56, v57
	global_store_dwordx2 v86, v[54:55], s[36:37] offset:512
	v_pk_mul_f32 v[54:55], v[62:63], v[88:89] op_sel_hi:[1,0]
	v_pk_mul_f32 v[56:57], v[64:65], v[88:89] op_sel_hi:[1,0]
	v_pk_fma_f32 v[54:55], v[26:27], v[54:55], v[30:31]
	v_pk_fma_f32 v[56:57], v[28:29], v[56:57], v[32:33]
	v_cvt_pk_bf16_f32 v54, v54, v55
	v_cvt_pk_bf16_f32 v55, v56, v57
	global_store_dwordx2 v86, v[54:55], s[36:37] offset:1024
	v_pk_mul_f32 v[54:55], v[66:67], v[88:89] op_sel_hi:[1,0]
	v_pk_mul_f32 v[56:57], v[68:69], v[88:89] op_sel_hi:[1,0]
	v_pk_fma_f32 v[56:57], v[40:41], v[56:57], v[48:49]
	v_pk_fma_f32 v[54:55], v[38:39], v[54:55], v[46:47]
	v_cvt_pk_bf16_f32 v54, v54, v55
	v_cvt_pk_bf16_f32 v55, v56, v57
	global_store_dwordx2 v86, v[54:55], s[36:37] offset:1536
	v_lshlrev_b32_e32 v54, 16, v108
	v_and_b32_e32 v55, 0xffff0000, v108
	v_lshlrev_b32_e32 v56, 16, v109
	v_and_b32_e32 v57, 0xffff0000, v109
	v_lshlrev_b32_e32 v58, 16, v110
	v_and_b32_e32 v59, 0xffff0000, v110
	v_lshlrev_b32_e32 v60, 16, v111
	v_and_b32_e32 v61, 0xffff0000, v111
	v_lshlrev_b32_e32 v62, 16, v112
	v_and_b32_e32 v63, 0xffff0000, v112
	v_lshlrev_b32_e32 v64, 16, v113
	v_and_b32_e32 v65, 0xffff0000, v113
	v_lshlrev_b32_e32 v66, 16, v114
	v_and_b32_e32 v67, 0xffff0000, v114
	v_lshlrev_b32_e32 v68, 16, v115
	v_and_b32_e32 v69, 0xffff0000, v115
	s_add_i32 s8, s8, s12
	s_add_u32 s36, s36, s13
	s_addc_u32 s37, s37, 0
	s_cmp_lt_i32 s8, 0x8000
	s_cbranch_scc0 .Ln7_ctx

; __device__ __forceinline__ unsigned pk2(float lo, float hi) { const f32x2_t v = {lo, hi}; return __builtin_bit_cast(unsigned, __builtin_convertvector(v, bf16x2_t)); }
; __device__ __forceinline__ float lane_xor(float v, int lane, int o) { return __int_as_float(__builtin_amdgcn_ds_bpermute((lane ^ o) << 2, __float_as_int(v))); }
; __device__ __forceinline__ float wave_sum(float v, int lane) {
; #pragma unroll
;     for (int o = 1; o < 64; o <<= 1) v += lane_xor(v, lane, o);
;     return v;
;     ...
;     for (int row = r_beg; row < r_end; row += NGW) {
;         const bool isc = row >= ML; const int mod = isc ? 4 : (row >> 13);
;         f32x4 v[4];
; #pragma unroll
;         for (int j = 0; j < 4; ++j) v[j] = vn[j];
;         if (row + NGW < r_end) { const int rn = row + NGW;
; #pragma unroll
;             for (int j = 0; j < 4; ++j) vn[j] = ld_row4(srcL, xb_in, srcC, rn, lane + 64 * j); }
;         if (xb_out && !isc) {
; #pragma unroll
;             for (int j = 0; j < 4; ++j) { u32x2 w; w.x = pk2(v[j].x, v[j].y); w.y = pk2(v[j].z, v[j].w); ((u32x2*)(xb_out + (size_t)row * DM))[lane + 64 * j] = w; } }
;         if (mod != cur_mod) { cur_mod = mod; const float* shp = mods_l + mod * 6144 + sh_off; const float* scp = mods_l + mod * 6144 + sc_off;
; #pragma unroll
;             for (int j = 0; j < 4; ++j) { gs[j] = ((const f32x4*)gam)[lane + 64 * j] * (((const f32x4*)scp)[lane + 64 * j] + 1.0f); shv[j] = ((const f32x4*)shp)[lane + 64 * j]; } }
;         if (isc && npart > 0) {
;             for (int ks = 0; ks < npart; ++ks) { const f32x4* pp = (const f32x4*)(part + ((size_t)ks * MC + (row - ML)) * DM);
; #pragma unroll
;                 for (int j = 0; j < 4; ++j) v[j] += pp[lane + 64 * j]; }
; #pragma unroll
;             for (int j = 0; j < 4; ++j) ((f32x4*)(srcC + (size_t)(row - ML) * DM))[lane + 64 * j] = v[j];
;         }
;         float s = 0.f;
; #pragma unroll
;         for (int j = 0; j < 4; ++j) s += (v[j].x * v[j].x + v[j].y * v[j].y) + (v[j].z * v[j].z + v[j].w * v[j].w);
;         s = wave_sum(s, lane); const float rstd = 1.0f / sqrtf(s * (1.0f / DM) + 1e-6f);
; #pragma unroll
;         for (int j = 0; j < 4; ++j) { const f32x4 y = v[j] * rstd * gs[j] + shv[j]; u32x2 w; w.x = pk2(y.x, y.y); w.y = pk2(y.z, y.w);
;             ((u32x2*)(H + (size_t)row * DM))[lane + 64 * j] = w; }
.Ln7_modokB:
	global_load_dwordx2 v[108:109], v86, s[34:35]
	global_load_dwordx2 v[110:111], v86, s[34:35] offset:512
	global_load_dwordx2 v[112:113], v86, s[34:35] offset:1024
	global_load_dwordx2 v[114:115], v86, s[34:35] offset:1536
	s_add_i32 s11, s46, s12
	s_cmp_lt_i32 s11, 0x8000
	s_cselect_b32 s46, s11, s46
	s_cselect_b32 s11, s13, 0
	s_add_u32 s34, s34, s11
	s_addc_u32 s35, s35, 0
	v_pk_mul_f32 v[90:91], v[56:57], v[56:57]
	v_pk_mul_f32 v[92:93], v[54:55], v[54:55]
	v_pk_mul_f32 v[4:5], v[60:61], v[60:61]
	v_pk_mul_f32 v[88:89], v[58:59], v[58:59]
	v_pk_mov_b32 v[94:95], v[92:93], v[90:91] op_sel:[1,0]
	v_mov_b32_e32 v93, v91
	v_pk_add_f32 v[90:91], v[94:95], v[92:93]
	v_pk_mov_b32 v[92:93], v[88:89], v[4:5] op_sel:[1,0]
	v_mov_b32_e32 v89, v5
	v_pk_add_f32 v[4:5], v[92:93], v[88:89]
	v_pk_add_f32 v[90:91], v[90:91], v[90:91] op_sel_hi:[0,1]
	v_pk_add_f32 v[4:5], v[4:5], v[4:5] op_sel_hi:[0,1]
	v_mul_f32_e32 v4, v62, v62
	v_pk_fma_f32 v[88:89], v[62:63], v[62:63], v[4:5] op_sel_hi:[1,1,0]
	v_mul_f32_e32 v4, v64, v64
	v_pk_fma_f32 v[92:93], v[64:65], v[64:65], v[4:5] op_sel_hi:[1,1,0]
	v_mul_f32_e32 v88, v66, v66
	v_mul_f32_e32 v92, v67, v67
	v_mul_f32_e32 v90, v68, v68
	v_mul_f32_e32 v4, v69, v69
	v_pk_add_f32 v[88:89], v[88:89], v[92:93]
	v_pk_add_f32 v[4:5], v[90:91], v[4:5]
	v_pk_add_f32 v[4:5], v[88:89], v[4:5]
	s_nop 0
	v_add_f32_e32 v3, v4, v5
	s_nop 1
	v_add_f32_dpp v3, v3, v3 quad_perm:[1,0,3,2] row_mask:0xf bank_mask:0xf
	s_nop 1
	v_add_f32_dpp v3, v3, v3 quad_perm:[2,3,0,1] row_mask:0xf bank_mask:0xf
	s_nop 1
	v_add_f32_dpp v3, v3, v3 row_half_mirror row_mask:0xf bank_mask:0xf
	s_nop 1
	v_add_f32_dpp v3, v3, v3 row_mirror row_mask:0xf bank_mask:0xf
	s_nop 1
	v_readlane_b32 s4, v3, 0
	v_readlane_b32 s5, v3, 16
	v_readlane_b32 s6, v3, 32
	v_readlane_b32 s7, v3, 48
	s_nop 1
	v_mov_b32_e32 v4, s4
	v_add_f32_e32 v4, s5, v4
	v_mov_b32_e32 v5, s6
	v_add_f32_e32 v5, s7, v5
	v_add_f32_e32 v3, v4, v5
	v_fmamk_f32 v3, v3, 0x3a800000, v238
	v_mul_f32_e32 v4, 0x4f800000, v3
	v_cmp_gt_f32_e32 vcc, s58, v3
	s_nop 1
	v_cndmask_b32_e32 v3, v3, v4, vcc
	v_sqrt_f32_e32 v4, v3
	s_nop 0
	v_add_u32_e32 v5, -1, v4
	v_add_u32_e32 v75, 1, v4
	v_fma_f32 v88, -v5, v4, v3
	v_fma_f32 v89, -v75, v4, v3
	v_cmp_ge_f32_e64 s[4:5], 0, v88
	s_nop 1
	v_cndmask_b32_e64 v4, v4, v5, s[4:5]
	v_cmp_lt_f32_e64 s[4:5], 0, v89
	s_nop 1
	v_cndmask_b32_e64 v4, v4, v75, s[4:5]
	v_mul_f32_e32 v5, 0x37800000, v4
	v_cndmask_b32_e32 v4, v4, v5, vcc
	v_cmp_class_f32_e32 vcc, v3, v248
	s_nop 1
	v_cndmask_b32_e32 v3, v4, v3, vcc
	v_div_scale_f32 v75, s[4:5], v3, v3, 1.0
	v_rcp_f32_e32 v88, v75
	v_div_scale_f32 v89, vcc, 1.0, v3, 1.0
	v_fma_f32 v90, -v75, v88, 1.0
	v_fmac_f32_e32 v88, v90, v88
	v_mul_f32_e32 v90, v89, v88
	v_fma_f32 v91, -v75, v90, v89
	v_fmac_f32_e32 v90, v91, v88
	v_fma_f32 v75, -v75, v90, v89
	v_div_fmas_f32 v75, v75, v88, v90
	v_div_fixup_f32 v88, v75, v3, 1.0
	s_waitcnt vmcnt(4)
	v_pk_mul_f32 v[54:55], v[54:55], v[88:89] op_sel_hi:[1,0]
	v_pk_mul_f32 v[56:57], v[56:57], v[88:89] op_sel_hi:[1,0]
	v_pk_fma_f32 v[54:55], v[6:7], v[54:55], v[10:11]
	v_pk_fma_f32 v[56:57], v[8:9], v[56:57], v[12:13]
	v_cvt_pk_bf16_f32 v54, v54, v55
	v_cvt_pk_bf16_f32 v55, v56, v57
	global_store_dwordx2 v86, v[54:55], s[36:37]
	v_pk_mul_f32 v[54:55], v[58:59], v[88:89] op_sel_hi:[1,0]
	v_pk_mul_f32 v[56:57], v[60:61], v[88:89] op_sel_hi:[1,0]
	v_pk_fma_f32 v[54:55], v[14:15], v[54:55], v[18:19]
	v_pk_fma_f32 v[56:57], v[16:17], v[56:57], v[20:21]
	v_cvt_pk_bf16_f32 v54, v54, v55
	v_cvt_pk_bf16_f32 v55, v56, v57
	global_store_dwordx2 v86, v[54:55], s[36:37] offset:512
	v_pk_mul_f32 v[54:55], v[62:63], v[88:89] op_sel_hi:[1,0]
	v_pk_mul_f32 v[56:57], v[64:65], v[88:89] op_sel_hi:[1,0]
	v_pk_fma_f32 v[54:55], v[26:27], v[54:55], v[30:31]
	v_pk_fma_f32 v[56:57], v[28:29], v[56:57], v[32:33]
	v_cvt_pk_bf16_f32 v54, v54, v55
	v_cvt_pk_bf16_f32 v55, v56, v57
	global_store_dwordx2 v86, v[54:55], s[36:37] offset:1024
	v_pk_mul_f32 v[54:55], v[66:67], v[88:89] op_sel_hi:[1,0]
	v_pk_mul_f32 v[56:57], v[68:69], v[88:89] op_sel_hi:[1,0]
	v_pk_fma_f32 v[56:57], v[40:41], v[56:57], v[48:49]
	v_pk_fma_f32 v[54:55], v[38:39], v[54:55], v[46:47]
	v_cvt_pk_bf16_f32 v54, v54, v55
	v_cvt_pk_bf16_f32 v55, v56, v57
	global_store_dwordx2 v86, v[54:55], s[36:37] offset:1536
	v_lshlrev_b32_e32 v54, 16, v100
	v_and_b32_e32 v55, 0xffff0000, v100
	v_lshlrev_b32_e32 v56, 16, v101
	v_and_b32_e32 v57, 0xffff0000, v101
	v_lshlrev_b32_e32 v58, 16, v102
	v_and_b32_e32 v59, 0xffff0000, v102
	v_lshlrev_b32_e32 v60, 16, v103
	v_and_b32_e32 v61, 0xffff0000, v103
	v_lshlrev_b32_e32 v62, 16, v104
	v_and_b32_e32 v63, 0xffff0000, v104
	v_lshlrev_b32_e32 v64, 16, v105
	v_and_b32_e32 v65, 0xffff0000, v105
	v_lshlrev_b32_e32 v66, 16, v106
	v_and_b32_e32 v67, 0xffff0000, v106
	v_lshlrev_b32_e32 v68, 16, v107
	v_and_b32_e32 v69, 0xffff0000, v107
	s_add_i32 s8, s8, s12
	s_add_u32 s36, s36, s13
	s_addc_u32 s37, s37, 0
	s_cmp_lt_i32 s8, 0x8000
	s_cbranch_scc0 .Ln7_ctx
	s_branch .Ln7_loopA

;     ...
;         if (mod != cur_mod) { cur_mod = mod; const float* shp = mods_l + mod * 6144 + sh_off; const float* scp = mods_l + mod * 6144 + sc_off;
; #pragma unroll
;             for (int j = 0; j < 4; ++j) { gs[j] = ((const f32x4*)gam)[lane + 64 * j] * (((const f32x4*)scp)[lane + 64 * j] + 1.0f); shv[j] = ((const f32x4*)shp)[lane + 64 * j]; } }
;         if (isc && npart > 0) {
;             for (int ks = 0; ks < npart; ++ks) { const f32x4* pp = (const f32x4*)(part + ((size_t)ks * MC + (row - ML)) * DM);
; #pragma unroll
;                 for (int j = 0; j < 4; ++j) v[j] += pp[lane + 64 * j]; }
; #pragma unroll
;             for (int j = 0; j < 4; ++j) ((f32x4*)(srcC + (size_t)(row - ML) * DM))[lane + 64 * j] = v[j];
.Ln7_ctxloop:
	s_add_u32 s54, s80, 0x36000
	s_addc_u32 s55, s81, 0
	s_add_u32 s42, s80, 0x37000
	s_addc_u32 s43, s81, 0
	global_load_dwordx4 v[10:13], v74, s[42:43]
	global_load_dwordx4 v[18:21], v74, s[42:43] offset:1024
	global_load_dwordx4 v[30:33], v74, s[42:43] offset:2048
	global_load_dwordx4 v[46:49], v74, s[42:43] offset:3072
	global_load_dwordx4 v[6:9], v74, s[0:1]
	global_load_dwordx4 v[14:17], v74, s[0:1] offset:1024
	global_load_dwordx4 v[26:29], v74, s[0:1] offset:2048
	global_load_dwordx4 v[38:41], v74, s[0:1] offset:3072
	s_add_i32 s6, s8, 0xffff8000
	s_mov_b32 s7, 0
	s_lshl_b64 s[6:7], s[6:7], 12
	s_add_u32 s84, s20, s6
	s_addc_u32 s85, s21, s7
	global_load_dwordx4 v[54:57], v74, s[84:85]
	global_load_dwordx4 v[58:61], v74, s[84:85] offset:1024
	global_load_dwordx4 v[62:65], v74, s[84:85] offset:2048
	global_load_dwordx4 v[66:69], v74, s[84:85] offset:3072
	s_waitcnt vmcnt(0)
	v_pk_add_f32 v[10:11], v[10:11], 1.0 op_sel_hi:[1,0]
	v_pk_add_f32 v[12:13], v[12:13], 1.0 op_sel_hi:[1,0]
	v_pk_mul_f32 v[6:7], v[6:7], v[10:11]
	v_pk_mul_f32 v[8:9], v[8:9], v[12:13]
	v_pk_add_f32 v[18:19], v[18:19], 1.0 op_sel_hi:[1,0]
	v_pk_add_f32 v[20:21], v[20:21], 1.0 op_sel_hi:[1,0]
	v_pk_mul_f32 v[14:15], v[14:15], v[18:19]
	v_pk_mul_f32 v[16:17], v[16:17], v[20:21]
	v_pk_add_f32 v[30:31], v[30:31], 1.0 op_sel_hi:[1,0]
	v_pk_add_f32 v[32:33], v[32:33], 1.0 op_sel_hi:[1,0]
	v_pk_mul_f32 v[26:27], v[26:27], v[30:31]
	v_pk_mul_f32 v[28:29], v[28:29], v[32:33]
	v_pk_add_f32 v[46:47], v[46:47], 1.0 op_sel_hi:[1,0]
	v_pk_add_f32 v[48:49], v[48:49], 1.0 op_sel_hi:[1,0]
	v_pk_mul_f32 v[38:39], v[38:39], v[46:47]
	v_pk_mul_f32 v[40:41], v[40:41], v[48:49]
	global_load_dwordx4 v[10:13], v74, s[54:55]
	global_load_dwordx4 v[18:21], v74, s[54:55] offset:1024
	global_load_dwordx4 v[30:33], v74, s[54:55] offset:2048
	global_load_dwordx4 v[46:49], v74, s[54:55] offset:3072
	s_add_u32 s86, s18, s6
	s_addc_u32 s87, s19, s7
	s_add_u32 s42, s86, 0x0
	s_addc_u32 s43, s87, 0
	global_load_dwordx4 v[116:119], v74, s[42:43]
	global_load_dwordx4 v[120:123], v74, s[42:43] offset:1024
	global_load_dwordx4 v[124:127], v74, s[42:43] offset:2048
	global_load_dwordx4 v[128:131], v74, s[42:43] offset:3072
	s_add_u32 s42, s86, 0x400000
	s_addc_u32 s43, s87, 0
	global_load_dwordx4 v[132:135], v74, s[42:43]
	global_load_dwordx4 v[136:139], v74, s[42:43] offset:1024
	global_load_dwordx4 v[140:143], v74, s[42:43] offset:2048
	global_load_dwordx4 v[144:147], v74, s[42:43] offset:3072
	s_add_u32 s42, s86, 0x800000
	s_addc_u32 s43, s87, 0
	global_load_dwordx4 v[148:151], v74, s[42:43]
	global_load_dwordx4 v[152:155], v74, s[42:43] offset:1024
	global_load_dwordx4 v[156:159], v74, s[42:43] offset:2048
	global_load_dwordx4 v[160:163], v74, s[42:43] offset:3072
	s_add_u32 s42, s86, 0xc00000
	s_addc_u32 s43, s87, 0
	global_load_dwordx4 v[164:167], v74, s[42:43]
	global_load_dwordx4 v[168:171], v74, s[42:43] offset:1024
	global_load_dwordx4 v[172:175], v74, s[42:43] offset:2048
	global_load_dwordx4 v[176:179], v74, s[42:43] offset:3072
	s_waitcnt vmcnt(0)
	v_pk_add_f32 v[54:55], v[54:55], v[116:117]
	v_pk_add_f32 v[56:57], v[56:57], v[118:119]
	v_pk_add_f32 v[58:59], v[58:59], v[120:121]
	v_pk_add_f32 v[60:61], v[60:61], v[122:123]
	v_pk_add_f32 v[62:63], v[62:63], v[124:125]
	v_pk_add_f32 v[64:65], v[64:65], v[126:127]
	v_pk_add_f32 v[66:67], v[66:67], v[128:129]
	v_pk_add_f32 v[68:69], v[68:69], v[130:131]
	v_pk_add_f32 v[54:55], v[54:55], v[132:133]
	v_pk_add_f32 v[56:57], v[56:57], v[134:135]
	v_pk_add_f32 v[58:59], v[58:59], v[136:137]
	v_pk_add_f32 v[60:61], v[60:61], v[138:139]
	v_pk_add_f32 v[62:63], v[62:63], v[140:141]
	v_pk_add_f32 v[64:65], v[64:65], v[142:143]
	v_pk_add_f32 v[66:67], v[66:67], v[144:145]
	v_pk_add_f32 v[68:69], v[68:69], v[146:147]
	v_pk_add_f32 v[54:55], v[54:55], v[148:149]
	v_pk_add_f32 v[56:57], v[56:57], v[150:151]
	v_pk_add_f32 v[58:59], v[58:59], v[152:153]
	v_pk_add_f32 v[60:61], v[60:61], v[154:155]
	v_pk_add_f32 v[62:63], v[62:63], v[156:157]
	v_pk_add_f32 v[64:65], v[64:65], v[158:159]
	v_pk_add_f32 v[66:67], v[66:67], v[160:161]
	v_pk_add_f32 v[68:69], v[68:69], v[162:163]
	v_pk_add_f32 v[54:55], v[54:55], v[164:165]
	v_pk_add_f32 v[56:57], v[56:57], v[166:167]
	v_pk_add_f32 v[58:59], v[58:59], v[168:169]
	v_pk_add_f32 v[60:61], v[60:61], v[170:171]
	v_pk_add_f32 v[62:63], v[62:63], v[172:173]
	v_pk_add_f32 v[64:65], v[64:65], v[174:175]
	v_pk_add_f32 v[66:67], v[66:67], v[176:177]
	v_pk_add_f32 v[68:69], v[68:69], v[178:179]
	s_add_u32 s42, s86, 0x1000000
	s_addc_u32 s43, s87, 0
	global_load_dwordx4 v[116:119], v74, s[42:43]
	global_load_dwordx4 v[120:123], v74, s[42:43] offset:1024
	global_load_dwordx4 v[124:127], v74, s[42:43] offset:2048
	global_load_dwordx4 v[128:131], v74, s[42:43] offset:3072
	s_add_u32 s42, s86, 0x1400000
	s_addc_u32 s43, s87, 0
	global_load_dwordx4 v[132:135], v74, s[42:43]
	global_load_dwordx4 v[136:139], v74, s[42:43] offset:1024
	global_load_dwordx4 v[140:143], v74, s[42:43] offset:2048
	global_load_dwordx4 v[144:147], v74, s[42:43] offset:3072
	s_add_u32 s42, s86, 0x1800000
	s_addc_u32 s43, s87, 0
	global_load_dwordx4 v[148:151], v74, s[42:43]
	global_load_dwordx4 v[152:155], v74, s[42:43] offset:1024
	global_load_dwordx4 v[156:159], v74, s[42:43] offset:2048
	global_load_dwordx4 v[160:163], v74, s[42:43] offset:3072
	s_add_u32 s42, s86, 0x1c00000
	s_addc_u32 s43, s87, 0
	global_load_dwordx4 v[164:167], v74, s[42:43]
	global_load_dwordx4 v[168:171], v74, s[42:43] offset:1024
	global_load_dwordx4 v[172:175], v74, s[42:43] offset:2048
	global_load_dwordx4 v[176:179], v74, s[42:43] offset:3072
	s_waitcnt vmcnt(0)
;     ...
;         if (isc && npart > 0) {
;             for (int ks = 0; ks < npart; ++ks) { const f32x4* pp = (const f32x4*)(part + ((size_t)ks * MC + (row - ML)) * DM);
; #pragma unroll
;                 for (int j = 0; j < 4; ++j) v[j] += pp[lane + 64 * j]; }
; #pragma unroll
;             for (int j = 0; j < 4; ++j) ((f32x4*)(srcC + (size_t)(row - ML) * DM))[lane + 64 * j] = v[j];
	v_pk_add_f32 v[54:55], v[54:55], v[116:117]
	v_pk_add_f32 v[56:57], v[56:57], v[118:119]
	v_pk_add_f32 v[58:59], v[58:59], v[120:121]
	v_pk_add_f32 v[60:61], v[60:61], v[122:123]
	v_pk_add_f32 v[62:63], v[62:63], v[124:125]
	v_pk_add_f32 v[64:65], v[64:65], v[126:127]
	v_pk_add_f32 v[66:67], v[66:67], v[128:129]
	v_pk_add_f32 v[68:69], v[68:69], v[130:131]
	v_pk_add_f32 v[54:55], v[54:55], v[132:133]
	v_pk_add_f32 v[56:57], v[56:57], v[134:135]
	v_pk_add_f32 v[58:59], v[58:59], v[136:137]
	v_pk_add_f32 v[60:61], v[60:61], v[138:139]
	v_pk_add_f32 v[62:63], v[62:63], v[140:141]
	v_pk_add_f32 v[64:65], v[64:65], v[142:143]
	v_pk_add_f32 v[66:67], v[66:67], v[144:145]
	v_pk_add_f32 v[68:69], v[68:69], v[146:147]
	v_pk_add_f32 v[54:55], v[54:55], v[148:149]
	v_pk_add_f32 v[56:57], v[56:57], v[150:151]
	v_pk_add_f32 v[58:59], v[58:59], v[152:153]
	v_pk_add_f32 v[60:61], v[60:61], v[154:155]
	v_pk_add_f32 v[62:63], v[62:63], v[156:157]
	v_pk_add_f32 v[64:65], v[64:65], v[158:159]
	v_pk_add_f32 v[66:67], v[66:67], v[160:161]
	v_pk_add_f32 v[68:69], v[68:69], v[162:163]
	v_pk_add_f32 v[54:55], v[54:55], v[164:165]
	v_pk_add_f32 v[56:57], v[56:57], v[166:167]
	v_pk_add_f32 v[58:59], v[58:59], v[168:169]
	v_pk_add_f32 v[60:61], v[60:61], v[170:171]
	v_pk_add_f32 v[62:63], v[62:63], v[172:173]
	v_pk_add_f32 v[64:65], v[64:65], v[174:175]
	v_pk_add_f32 v[66:67], v[66:67], v[176:177]
	v_pk_add_f32 v[68:69], v[68:69], v[178:179]
	s_add_u32 s42, s86, 0x2000000
	s_addc_u32 s43, s87, 0
	global_load_dwordx4 v[116:119], v74, s[42:43]
	global_load_dwordx4 v[120:123], v74, s[42:43] offset:1024
	global_load_dwordx4 v[124:127], v74, s[42:43] offset:2048
	global_load_dwordx4 v[128:131], v74, s[42:43] offset:3072
	s_add_u32 s42, s86, 0x2400000
	s_addc_u32 s43, s87, 0
	global_load_dwordx4 v[132:135], v74, s[42:43]
	global_load_dwordx4 v[136:139], v74, s[42:43] offset:1024
	global_load_dwordx4 v[140:143], v74, s[42:43] offset:2048
	global_load_dwordx4 v[144:147], v74, s[42:43] offset:3072
	s_add_u32 s42, s86, 0x2800000
	s_addc_u32 s43, s87, 0
	global_load_dwordx4 v[148:151], v74, s[42:43]
	global_load_dwordx4 v[152:155], v74, s[42:43] offset:1024
	global_load_dwordx4 v[156:159], v74, s[42:43] offset:2048
	global_load_dwordx4 v[160:163], v74, s[42:43] offset:3072
	s_waitcnt vmcnt(0)
; __device__ __forceinline__ unsigned pk2(float lo, float hi) { const f32x2_t v = {lo, hi}; return __builtin_bit_cast(unsigned, __builtin_convertvector(v, bf16x2_t)); }
; __device__ __forceinline__ float lane_xor(float v, int lane, int o) { return __int_as_float(__builtin_amdgcn_ds_bpermute((lane ^ o) << 2, __float_as_int(v))); }
; __device__ __forceinline__ float wave_sum(float v, int lane) {
; #pragma unroll
;     for (int o = 1; o < 64; o <<= 1) v += lane_xor(v, lane, o);
;     return v;
;     ...
;             for (int j = 0; j < 4; ++j) ((f32x4*)(srcC + (size_t)(row - ML) * DM))[lane + 64 * j] = v[j];
;         }
;         float s = 0.f;
; #pragma unroll
;         for (int j = 0; j < 4; ++j) s += (v[j].x * v[j].x + v[j].y * v[j].y) + (v[j].z * v[j].z + v[j].w * v[j].w);
;         s = wave_sum(s, lane); const float rstd = 1.0f / sqrtf(s * (1.0f / DM) + 1e-6f);
; #pragma unroll
;         for (int j = 0; j < 4; ++j) { const f32x4 y = v[j] * rstd * gs[j] + shv[j]; u32x2 w; w.x = pk2(y.x, y.y); w.y = pk2(y.z, y.w);
;             ((u32x2*)(H + (size_t)row * DM))[lane + 64 * j] = w; }
	v_pk_add_f32 v[54:55], v[54:55], v[116:117]
	v_pk_add_f32 v[56:57], v[56:57], v[118:119]
	v_pk_add_f32 v[58:59], v[58:59], v[120:121]
	v_pk_add_f32 v[60:61], v[60:61], v[122:123]
	v_pk_add_f32 v[62:63], v[62:63], v[124:125]
	v_pk_add_f32 v[64:65], v[64:65], v[126:127]
	v_pk_add_f32 v[66:67], v[66:67], v[128:129]
	v_pk_add_f32 v[68:69], v[68:69], v[130:131]
	v_pk_add_f32 v[54:55], v[54:55], v[132:133]
	v_pk_add_f32 v[56:57], v[56:57], v[134:135]
	v_pk_add_f32 v[58:59], v[58:59], v[136:137]
	v_pk_add_f32 v[60:61], v[60:61], v[138:139]
	v_pk_add_f32 v[62:63], v[62:63], v[140:141]
	v_pk_add_f32 v[64:65], v[64:65], v[142:143]
	v_pk_add_f32 v[66:67], v[66:67], v[144:145]
	v_pk_add_f32 v[68:69], v[68:69], v[146:147]
	v_pk_add_f32 v[54:55], v[54:55], v[148:149]
	v_pk_add_f32 v[56:57], v[56:57], v[150:151]
	v_pk_add_f32 v[58:59], v[58:59], v[152:153]
	v_pk_add_f32 v[60:61], v[60:61], v[154:155]
	v_pk_add_f32 v[62:63], v[62:63], v[156:157]
	v_pk_add_f32 v[64:65], v[64:65], v[158:159]
	v_pk_add_f32 v[66:67], v[66:67], v[160:161]
	v_pk_add_f32 v[68:69], v[68:69], v[162:163]
	global_store_dwordx4 v74, v[54:57], s[84:85]
	global_store_dwordx4 v74, v[58:61], s[84:85] offset:1024
	global_store_dwordx4 v74, v[62:65], s[84:85] offset:2048
	global_store_dwordx4 v74, v[66:69], s[84:85] offset:3072
	s_ashr_i32 s11, s8, 31
	s_mov_b32 s6, s8
	s_mov_b32 s7, s11
	s_lshl_b64 s[6:7], s[6:7], 11
	s_add_u32 s36, s75, s6
	s_addc_u32 s37, s76, s7
	v_pk_mul_f32 v[90:91], v[56:57], v[56:57]
	v_pk_mul_f32 v[92:93], v[54:55], v[54:55]
	v_pk_mul_f32 v[4:5], v[60:61], v[60:61]
	v_pk_mul_f32 v[88:89], v[58:59], v[58:59]
	v_pk_mov_b32 v[94:95], v[92:93], v[90:91] op_sel:[1,0]
	v_mov_b32_e32 v93, v91
	v_pk_add_f32 v[90:91], v[94:95], v[92:93]
	v_pk_mov_b32 v[92:93], v[88:89], v[4:5] op_sel:[1,0]
	v_mov_b32_e32 v89, v5
	v_pk_add_f32 v[4:5], v[92:93], v[88:89]
	v_pk_add_f32 v[90:91], v[90:91], v[90:91] op_sel_hi:[0,1]
	v_pk_add_f32 v[4:5], v[4:5], v[4:5] op_sel_hi:[0,1]
	v_mul_f32_e32 v4, v62, v62
	v_pk_fma_f32 v[88:89], v[62:63], v[62:63], v[4:5] op_sel_hi:[1,1,0]
	v_mul_f32_e32 v4, v64, v64
	v_pk_fma_f32 v[92:93], v[64:65], v[64:65], v[4:5] op_sel_hi:[1,1,0]
	v_mul_f32_e32 v88, v66, v66
	v_mul_f32_e32 v92, v67, v67
	v_mul_f32_e32 v90, v68, v68
	v_mul_f32_e32 v4, v69, v69
	v_pk_add_f32 v[88:89], v[88:89], v[92:93]
	v_pk_add_f32 v[4:5], v[90:91], v[4:5]
	v_pk_add_f32 v[4:5], v[88:89], v[4:5]
	s_nop 0
	v_add_f32_e32 v3, v4, v5
	s_nop 1
	v_add_f32_dpp v3, v3, v3 quad_perm:[1,0,3,2] row_mask:0xf bank_mask:0xf
	s_nop 1
	v_add_f32_dpp v3, v3, v3 quad_perm:[2,3,0,1] row_mask:0xf bank_mask:0xf
	s_nop 1
	v_add_f32_dpp v3, v3, v3 row_half_mirror row_mask:0xf bank_mask:0xf
	s_nop 1
	v_add_f32_dpp v3, v3, v3 row_mirror row_mask:0xf bank_mask:0xf
	s_nop 1
	v_readlane_b32 s4, v3, 0
	v_readlane_b32 s5, v3, 16
	v_readlane_b32 s6, v3, 32
	v_readlane_b32 s7, v3, 48
	s_nop 1
	v_mov_b32_e32 v4, s4
	v_add_f32_e32 v4, s5, v4
	v_mov_b32_e32 v5, s6
	v_add_f32_e32 v5, s7, v5
	v_add_f32_e32 v3, v4, v5
	v_fmamk_f32 v3, v3, 0x3a800000, v238
	v_mul_f32_e32 v4, 0x4f800000, v3
	v_cmp_gt_f32_e32 vcc, s58, v3
	s_nop 1
	v_cndmask_b32_e32 v3, v3, v4, vcc
	v_sqrt_f32_e32 v4, v3
	s_nop 0
	v_add_u32_e32 v5, -1, v4
	v_add_u32_e32 v75, 1, v4
	v_fma_f32 v88, -v5, v4, v3
	v_fma_f32 v89, -v75, v4, v3
	v_cmp_ge_f32_e64 s[4:5], 0, v88
	s_nop 1
	v_cndmask_b32_e64 v4, v4, v5, s[4:5]
	v_cmp_lt_f32_e64 s[4:5], 0, v89
	s_nop 1
	v_cndmask_b32_e64 v4, v4, v75, s[4:5]
	v_mul_f32_e32 v5, 0x37800000, v4
	v_cndmask_b32_e32 v4, v4, v5, vcc
	v_cmp_class_f32_e32 vcc, v3, v248
	s_nop 1
	v_cndmask_b32_e32 v3, v4, v3, vcc
	v_div_scale_f32 v75, s[4:5], v3, v3, 1.0
	v_rcp_f32_e32 v88, v75
	v_div_scale_f32 v89, vcc, 1.0, v3, 1.0
	v_fma_f32 v90, -v75, v88, 1.0
	v_fmac_f32_e32 v88, v90, v88
	v_mul_f32_e32 v90, v89, v88
	v_fma_f32 v91, -v75, v90, v89
	v_fmac_f32_e32 v90, v91, v88
	v_fma_f32 v75, -v75, v90, v89
	v_div_fmas_f32 v75, v75, v88, v90
	v_div_fixup_f32 v88, v75, v3, 1.0
	v_pk_mul_f32 v[54:55], v[54:55], v[88:89] op_sel_hi:[1,0]
	v_pk_mul_f32 v[56:57], v[56:57], v[88:89] op_sel_hi:[1,0]
	v_pk_fma_f32 v[54:55], v[6:7], v[54:55], v[10:11]
	v_pk_fma_f32 v[56:57], v[8:9], v[56:57], v[12:13]
	v_cvt_pk_bf16_f32 v54, v54, v55
	v_cvt_pk_bf16_f32 v55, v56, v57
	global_store_dwordx2 v86, v[54:55], s[36:37]
	v_pk_mul_f32 v[54:55], v[58:59], v[88:89] op_sel_hi:[1,0]
	v_pk_mul_f32 v[56:57], v[60:61], v[88:89] op_sel_hi:[1,0]
	v_pk_fma_f32 v[54:55], v[14:15], v[54:55], v[18:19]
	v_pk_fma_f32 v[56:57], v[16:17], v[56:57], v[20:21]
	v_cvt_pk_bf16_f32 v54, v54, v55
	v_cvt_pk_bf16_f32 v55, v56, v57
	global_store_dwordx2 v86, v[54:55], s[36:37] offset:512
	v_pk_mul_f32 v[54:55], v[62:63], v[88:89] op_sel_hi:[1,0]
	v_pk_mul_f32 v[56:57], v[64:65], v[88:89] op_sel_hi:[1,0]
	v_pk_fma_f32 v[54:55], v[26:27], v[54:55], v[30:31]
	v_pk_fma_f32 v[56:57], v[28:29], v[56:57], v[32:33]
	v_cvt_pk_bf16_f32 v54, v54, v55
	v_cvt_pk_bf16_f32 v55, v56, v57
	global_store_dwordx2 v86, v[54:55], s[36:37] offset:1024
	v_pk_mul_f32 v[54:55], v[66:67], v[88:89] op_sel_hi:[1,0]
	v_pk_mul_f32 v[56:57], v[68:69], v[88:89] op_sel_hi:[1,0]
	v_pk_fma_f32 v[56:57], v[40:41], v[56:57], v[48:49]
	v_pk_fma_f32 v[54:55], v[38:39], v[54:55], v[46:47]
	v_cvt_pk_bf16_f32 v54, v54, v55
	v_cvt_pk_bf16_f32 v55, v56, v57
	global_store_dwordx2 v86, v[54:55], s[36:37] offset:1536
	s_add_i32 s8, s8, s12
	s_cmp_lt_i32 s8, 0x8400
	s_cbranch_scc1 .Ln7_ctxloop

; __global__ void __launch_bounds__(NTHR, 2) mk_fwd(Args a) {
;     ...
;                     for (int row = gw; row < ML; row += NGW) {
;                         f32x4* xr = (f32x4*)(xres + (size_t)row * DM); f32x4 v[4]; float s = 0.f;
; #pragma unroll
;                         for (int j = 0; j < 4; ++j) { v[j] = ld_row4(nullptr, XB, nullptr, row, lane + 64 * j); s += (v[j].x * v[j].x + v[j].y * v[j].y) + (v[j].z * v[j].z + v[j].w * v[j].w); }
;                         s = wave_sum(s, lane); const float rstd = 1.0f / sqrtf(s * (1.0f / DM) + 1e-6f);
; #pragma unroll
;                         for (int j = 0; j < 4; ++j) xr[lane + 64 * j] = v[j] * rstd * ((const f32x4*)final_g)[lane + 64 * j];
;                     }
.Lnf_loopA:
	global_load_dwordx2 v[100:101], v86, s[34:35]
	global_load_dwordx2 v[102:103], v86, s[34:35] offset:512
	global_load_dwordx2 v[104:105], v86, s[34:35] offset:1024
	global_load_dwordx2 v[106:107], v86, s[34:35] offset:1536
	s_add_i32 s11, s46, s12
	s_cmp_lt_i32 s11, 0x8000
	s_cselect_b32 s46, s11, s46
	s_cselect_b32 s11, s13, 0
	s_add_u32 s34, s34, s11
	s_addc_u32 s35, s35, 0
	v_pk_mul_f32 v[90:91], v[56:57], v[56:57]
	v_pk_mul_f32 v[92:93], v[54:55], v[54:55]
	v_pk_mul_f32 v[4:5], v[60:61], v[60:61]
	v_pk_mul_f32 v[88:89], v[58:59], v[58:59]
	v_pk_mov_b32 v[94:95], v[92:93], v[90:91] op_sel:[1,0]
	v_mov_b32_e32 v93, v91
	v_pk_add_f32 v[90:91], v[94:95], v[92:93]
	v_pk_mov_b32 v[92:93], v[88:89], v[4:5] op_sel:[1,0]
	v_mov_b32_e32 v89, v5
	v_pk_add_f32 v[4:5], v[92:93], v[88:89]
	v_pk_add_f32 v[90:91], v[90:91], v[90:91] op_sel_hi:[0,1]
	v_pk_add_f32 v[4:5], v[4:5], v[4:5] op_sel_hi:[0,1]
	v_mul_f32_e32 v4, v62, v62
	v_pk_fma_f32 v[88:89], v[62:63], v[62:63], v[4:5] op_sel_hi:[1,1,0]
	v_mul_f32_e32 v4, v64, v64
	v_pk_fma_f32 v[92:93], v[64:65], v[64:65], v[4:5] op_sel_hi:[1,1,0]
	v_mul_f32_e32 v88, v66, v66
	v_mul_f32_e32 v92, v67, v67
	v_mul_f32_e32 v90, v68, v68
	v_mul_f32_e32 v4, v69, v69
	v_pk_add_f32 v[88:89], v[88:89], v[92:93]
	v_pk_add_f32 v[4:5], v[90:91], v[4:5]
	v_pk_add_f32 v[4:5], v[88:89], v[4:5]
	s_nop 0
	v_add_f32_e32 v3, v4, v5
	s_nop 1
	v_add_f32_dpp v3, v3, v3 quad_perm:[1,0,3,2] row_mask:0xf bank_mask:0xf
	s_nop 1
	v_add_f32_dpp v3, v3, v3 quad_perm:[2,3,0,1] row_mask:0xf bank_mask:0xf
	s_nop 1
	v_add_f32_dpp v3, v3, v3 row_half_mirror row_mask:0xf bank_mask:0xf
	s_nop 1
	v_add_f32_dpp v3, v3, v3 row_mirror row_mask:0xf bank_mask:0xf
	s_nop 1
	v_readlane_b32 s4, v3, 0
	v_readlane_b32 s5, v3, 16
	v_readlane_b32 s6, v3, 32
	v_readlane_b32 s7, v3, 48
	s_nop 1
	v_mov_b32_e32 v4, s4
	v_add_f32_e32 v4, s5, v4
	v_mov_b32_e32 v5, s6
	v_add_f32_e32 v5, s7, v5
	v_add_f32_e32 v3, v4, v5
	v_fmamk_f32 v3, v3, 0x3a800000, v238
	v_mul_f32_e32 v4, 0x4f800000, v3
	v_cmp_gt_f32_e32 vcc, s58, v3
	s_nop 1
	v_cndmask_b32_e32 v3, v3, v4, vcc
	v_sqrt_f32_e32 v4, v3
	s_nop 0
	v_add_u32_e32 v5, -1, v4
	v_add_u32_e32 v75, 1, v4
	v_fma_f32 v88, -v5, v4, v3
	v_fma_f32 v89, -v75, v4, v3
	v_cmp_ge_f32_e64 s[4:5], 0, v88
	s_nop 1
	v_cndmask_b32_e64 v4, v4, v5, s[4:5]
	v_cmp_lt_f32_e64 s[4:5], 0, v89
	s_nop 1
	v_cndmask_b32_e64 v4, v4, v75, s[4:5]
	v_mul_f32_e32 v5, 0x37800000, v4
	v_cndmask_b32_e32 v4, v4, v5, vcc
	v_cmp_class_f32_e32 vcc, v3, v248
	s_nop 1
	v_cndmask_b32_e32 v3, v4, v3, vcc
	v_div_scale_f32 v75, s[4:5], v3, v3, 1.0
	v_rcp_f32_e32 v88, v75
	v_div_scale_f32 v89, vcc, 1.0, v3, 1.0
	v_fma_f32 v90, -v75, v88, 1.0
	v_fmac_f32_e32 v88, v90, v88
	v_mul_f32_e32 v90, v89, v88
	v_fma_f32 v91, -v75, v90, v89
	v_fmac_f32_e32 v90, v91, v88
	v_fma_f32 v75, -v75, v90, v89
	v_div_fmas_f32 v75, v75, v88, v90
	v_div_fixup_f32 v88, v75, v3, 1.0
	s_waitcnt vmcnt(4)
	v_pk_mul_f32 v[54:55], v[54:55], v[88:89] op_sel_hi:[1,0]
	v_pk_mul_f32 v[56:57], v[56:57], v[88:89] op_sel_hi:[1,0]
	v_pk_mul_f32 v[54:55], v[54:55], v[6:7]
	v_pk_mul_f32 v[56:57], v[56:57], v[8:9]
	global_store_dwordx4 v74, v[54:57], s[36:37]
	v_pk_mul_f32 v[58:59], v[58:59], v[88:89] op_sel_hi:[1,0]
	v_pk_mul_f32 v[60:61], v[60:61], v[88:89] op_sel_hi:[1,0]
	v_pk_mul_f32 v[58:59], v[58:59], v[14:15]
	v_pk_mul_f32 v[60:61], v[60:61], v[16:17]
	global_store_dwordx4 v74, v[58:61], s[36:37] offset:1024
	v_pk_mul_f32 v[62:63], v[62:63], v[88:89] op_sel_hi:[1,0]
	v_pk_mul_f32 v[64:65], v[64:65], v[88:89] op_sel_hi:[1,0]
	v_pk_mul_f32 v[62:63], v[62:63], v[26:27]
	v_pk_mul_f32 v[64:65], v[64:65], v[28:29]
	global_store_dwordx4 v74, v[62:65], s[36:37] offset:2048
	v_pk_mul_f32 v[66:67], v[66:67], v[88:89] op_sel_hi:[1,0]
	v_pk_mul_f32 v[68:69], v[68:69], v[88:89] op_sel_hi:[1,0]
	v_pk_mul_f32 v[66:67], v[66:67], v[38:39]
	v_pk_mul_f32 v[68:69], v[68:69], v[40:41]
	global_store_dwordx4 v74, v[66:69], s[36:37] offset:3072
	s_nop 1
	v_lshlrev_b32_e32 v54, 16, v108
	v_and_b32_e32 v55, 0xffff0000, v108
	v_lshlrev_b32_e32 v56, 16, v109
	v_and_b32_e32 v57, 0xffff0000, v109
	v_lshlrev_b32_e32 v58, 16, v110
	v_and_b32_e32 v59, 0xffff0000, v110
	v_lshlrev_b32_e32 v60, 16, v111
	v_and_b32_e32 v61, 0xffff0000, v111
	v_lshlrev_b32_e32 v62, 16, v112
	v_and_b32_e32 v63, 0xffff0000, v112
	v_lshlrev_b32_e32 v64, 16, v113
	v_and_b32_e32 v65, 0xffff0000, v113
	v_lshlrev_b32_e32 v66, 16, v114
	v_and_b32_e32 v67, 0xffff0000, v114
	v_lshlrev_b32_e32 v68, 16, v115
	v_and_b32_e32 v69, 0xffff0000, v115
	s_add_i32 s8, s8, s12
	s_add_u32 s36, s36, s3
	s_addc_u32 s37, s37, 0
	s_cmp_lt_i32 s8, 0x8000
	s_cbranch_scc0 .Lnf_done
; __global__ void __launch_bounds__(NTHR, 2) mk_fwd(Args a) {
;     ...
;                     for (int row = gw; row < ML; row += NGW) {
;                         f32x4* xr = (f32x4*)(xres + (size_t)row * DM); f32x4 v[4]; float s = 0.f;
; #pragma unroll
;                         for (int j = 0; j < 4; ++j) { v[j] = ld_row4(nullptr, XB, nullptr, row, lane + 64 * j); s += (v[j].x * v[j].x + v[j].y * v[j].y) + (v[j].z * v[j].z + v[j].w * v[j].w); }
;                         s = wave_sum(s, lane); const float rstd = 1.0f / sqrtf(s * (1.0f / DM) + 1e-6f);
; #pragma unroll
;                         for (int j = 0; j < 4; ++j) xr[lane + 64 * j] = v[j] * rstd * ((const f32x4*)final_g)[lane + 64 * j];
;                     }
.Lnf_loopB:
	global_load_dwordx2 v[108:109], v86, s[34:35]
	global_load_dwordx2 v[110:111], v86, s[34:35] offset:512
	global_load_dwordx2 v[112:113], v86, s[34:35] offset:1024
	global_load_dwordx2 v[114:115], v86, s[34:35] offset:1536
	s_add_i32 s11, s46, s12
	s_cmp_lt_i32 s11, 0x8000
	s_cselect_b32 s46, s11, s46
	s_cselect_b32 s11, s13, 0
	s_add_u32 s34, s34, s11
	s_addc_u32 s35, s35, 0
	v_pk_mul_f32 v[90:91], v[56:57], v[56:57]
	v_pk_mul_f32 v[92:93], v[54:55], v[54:55]
	v_pk_mul_f32 v[4:5], v[60:61], v[60:61]
	v_pk_mul_f32 v[88:89], v[58:59], v[58:59]
	v_pk_mov_b32 v[94:95], v[92:93], v[90:91] op_sel:[1,0]
	v_mov_b32_e32 v93, v91
	v_pk_add_f32 v[90:91], v[94:95], v[92:93]
	v_pk_mov_b32 v[92:93], v[88:89], v[4:5] op_sel:[1,0]
	v_mov_b32_e32 v89, v5
	v_pk_add_f32 v[4:5], v[92:93], v[88:89]
	v_pk_add_f32 v[90:91], v[90:91], v[90:91] op_sel_hi:[0,1]
	v_pk_add_f32 v[4:5], v[4:5], v[4:5] op_sel_hi:[0,1]
	v_mul_f32_e32 v4, v62, v62
	v_pk_fma_f32 v[88:89], v[62:63], v[62:63], v[4:5] op_sel_hi:[1,1,0]
	v_mul_f32_e32 v4, v64, v64
	v_pk_fma_f32 v[92:93], v[64:65], v[64:65], v[4:5] op_sel_hi:[1,1,0]
	v_mul_f32_e32 v88, v66, v66
	v_mul_f32_e32 v92, v67, v67
	v_mul_f32_e32 v90, v68, v68
	v_mul_f32_e32 v4, v69, v69
	v_pk_add_f32 v[88:89], v[88:89], v[92:93]
	v_pk_add_f32 v[4:5], v[90:91], v[4:5]
	v_pk_add_f32 v[4:5], v[88:89], v[4:5]
	s_nop 0
	v_add_f32_e32 v3, v4, v5
	s_nop 1
	v_add_f32_dpp v3, v3, v3 quad_perm:[1,0,3,2] row_mask:0xf bank_mask:0xf
	s_nop 1
	v_add_f32_dpp v3, v3, v3 quad_perm:[2,3,0,1] row_mask:0xf bank_mask:0xf
	s_nop 1
	v_add_f32_dpp v3, v3, v3 row_half_mirror row_mask:0xf bank_mask:0xf
	s_nop 1
	v_add_f32_dpp v3, v3, v3 row_mirror row_mask:0xf bank_mask:0xf
	s_nop 1
	v_readlane_b32 s4, v3, 0
	v_readlane_b32 s5, v3, 16
	v_readlane_b32 s6, v3, 32
	v_readlane_b32 s7, v3, 48
	s_nop 1
	v_mov_b32_e32 v4, s4
	v_add_f32_e32 v4, s5, v4
	v_mov_b32_e32 v5, s6
	v_add_f32_e32 v5, s7, v5
	v_add_f32_e32 v3, v4, v5
	v_fmamk_f32 v3, v3, 0x3a800000, v238
	v_mul_f32_e32 v4, 0x4f800000, v3
	v_cmp_gt_f32_e32 vcc, s58, v3
	s_nop 1
	v_cndmask_b32_e32 v3, v3, v4, vcc
	v_sqrt_f32_e32 v4, v3
	s_nop 0
	v_add_u32_e32 v5, -1, v4
	v_add_u32_e32 v75, 1, v4
	v_fma_f32 v88, -v5, v4, v3
	v_fma_f32 v89, -v75, v4, v3
	v_cmp_ge_f32_e64 s[4:5], 0, v88
	s_nop 1
	v_cndmask_b32_e64 v4, v4, v5, s[4:5]
	v_cmp_lt_f32_e64 s[4:5], 0, v89
	s_nop 1
	v_cndmask_b32_e64 v4, v4, v75, s[4:5]
	v_mul_f32_e32 v5, 0x37800000, v4
	v_cndmask_b32_e32 v4, v4, v5, vcc
	v_cmp_class_f32_e32 vcc, v3, v248
	s_nop 1
	v_cndmask_b32_e32 v3, v4, v3, vcc
	v_div_scale_f32 v75, s[4:5], v3, v3, 1.0
	v_rcp_f32_e32 v88, v75
	v_div_scale_f32 v89, vcc, 1.0, v3, 1.0
	v_fma_f32 v90, -v75, v88, 1.0
	v_fmac_f32_e32 v88, v90, v88
	v_mul_f32_e32 v90, v89, v88
	v_fma_f32 v91, -v75, v90, v89
	v_fmac_f32_e32 v90, v91, v88
	v_fma_f32 v75, -v75, v90, v89
	v_div_fmas_f32 v75, v75, v88, v90
	v_div_fixup_f32 v88, v75, v3, 1.0
	s_waitcnt vmcnt(4)
	v_pk_mul_f32 v[54:55], v[54:55], v[88:89] op_sel_hi:[1,0]
	v_pk_mul_f32 v[56:57], v[56:57], v[88:89] op_sel_hi:[1,0]
	v_pk_mul_f32 v[54:55], v[54:55], v[6:7]
	v_pk_mul_f32 v[56:57], v[56:57], v[8:9]
	global_store_dwordx4 v74, v[54:57], s[36:37]
	v_pk_mul_f32 v[58:59], v[58:59], v[88:89] op_sel_hi:[1,0]
	v_pk_mul_f32 v[60:61], v[60:61], v[88:89] op_sel_hi:[1,0]
	v_pk_mul_f32 v[58:59], v[58:59], v[14:15]
	v_pk_mul_f32 v[60:61], v[60:61], v[16:17]
	global_store_dwordx4 v74, v[58:61], s[36:37] offset:1024
	v_pk_mul_f32 v[62:63], v[62:63], v[88:89] op_sel_hi:[1,0]
	v_pk_mul_f32 v[64:65], v[64:65], v[88:89] op_sel_hi:[1,0]
	v_pk_mul_f32 v[62:63], v[62:63], v[26:27]
	v_pk_mul_f32 v[64:65], v[64:65], v[28:29]
	global_store_dwordx4 v74, v[62:65], s[36:37] offset:2048
	v_pk_mul_f32 v[66:67], v[66:67], v[88:89] op_sel_hi:[1,0]
	v_pk_mul_f32 v[68:69], v[68:69], v[88:89] op_sel_hi:[1,0]
	v_pk_mul_f32 v[66:67], v[66:67], v[38:39]
	v_pk_mul_f32 v[68:69], v[68:69], v[40:41]
	global_store_dwordx4 v74, v[66:69], s[36:37] offset:3072
	s_nop 1
	v_lshlrev_b32_e32 v54, 16, v100
	v_and_b32_e32 v55, 0xffff0000, v100
	v_lshlrev_b32_e32 v56, 16, v101
	v_and_b32_e32 v57, 0xffff0000, v101
	v_lshlrev_b32_e32 v58, 16, v102
	v_and_b32_e32 v59, 0xffff0000, v102
	v_lshlrev_b32_e32 v60, 16, v103
	v_and_b32_e32 v61, 0xffff0000, v103
	v_lshlrev_b32_e32 v62, 16, v104
	v_and_b32_e32 v63, 0xffff0000, v104
	v_lshlrev_b32_e32 v64, 16, v105
	v_and_b32_e32 v65, 0xffff0000, v105
	v_lshlrev_b32_e32 v66, 16, v106
	v_and_b32_e32 v67, 0xffff0000, v106
	v_lshlrev_b32_e32 v68, 16, v107
	v_and_b32_e32 v69, 0xffff0000, v107
	s_add_i32 s8, s8, s12
	s_add_u32 s36, s36, s3
	s_addc_u32 s37, s37, 0
	s_cmp_lt_i32 s8, 0x8000
	s_cbranch_scc0 .Lnf_done
	s_branch .Lnf_loopA

; __device__ __forceinline__ unsigned pk2(float lo, float hi) { const f32x2_t v = {lo, hi}; return __builtin_bit_cast(unsigned, __builtin_convertvector(v, bf16x2_t)); }
;     ...
;     for (int row = r_beg; row < r_end; row += NGW) {
;         const bool isc = row >= ML; const int mod = isc ? 4 : (row >> 13);
;         f32x4 v[4];
; #pragma unroll
;         for (int j = 0; j < 4; ++j) v[j] = vn[j];
;         if (row + NGW < r_end) { const int rn = row + NGW;
; #pragma unroll
;             for (int j = 0; j < 4; ++j) vn[j] = ld_row4(srcL, xb_in, srcC, rn, lane + 64 * j); }
;         if (xb_out && !isc) {
; #pragma unroll
;             for (int j = 0; j < 4; ++j) { u32x2 w; w.x = pk2(v[j].x, v[j].y); w.y = pk2(v[j].z, v[j].w); ((u32x2*)(xb_out + (size_t)row * DM))[lane + 64 * j] = w; } }
;         if (mod != cur_mod) { cur_mod = mod; const float* shp = mods_l + mod * 6144 + sh_off; const float* scp = mods_l + mod * 6144 + sc_off;
; #pragma unroll
;             for (int j = 0; j < 4; ++j) { gs[j] = ((const f32x4*)gam)[lane + 64 * j] * (((const f32x4*)scp)[lane + 64 * j] + 1.0f); shv[j] = ((const f32x4*)shp)[lane + 64 * j]; } }
;         if (isc && npart > 0) {
;             for (int ks = 0; ks < npart; ++ks) { const f32x4* pp = (const f32x4*)(part + ((size_t)ks * MC + (row - ML)) * DM);
; #pragma unroll
;                 for (int j = 0; j < 4; ++j) v[j] += pp[lane + 64 * j]; }
.Ln4_ctxloop:
	s_add_u32 s54, s80, 0x1b000
	s_addc_u32 s55, s81, 0
	s_add_u32 s42, s80, 0x1c000
	s_addc_u32 s43, s81, 0
	global_load_dwordx4 v[10:13], v74, s[42:43]
	global_load_dwordx4 v[18:21], v74, s[42:43] offset:1024
	global_load_dwordx4 v[30:33], v74, s[42:43] offset:2048
	global_load_dwordx4 v[46:49], v74, s[42:43] offset:3072
	global_load_dwordx4 v[6:9], v74, s[0:1]
	global_load_dwordx4 v[14:17], v74, s[0:1] offset:1024
	global_load_dwordx4 v[26:29], v74, s[0:1] offset:2048
	global_load_dwordx4 v[38:41], v74, s[0:1] offset:3072
	s_add_i32 s6, s8, 0xffff8000
	s_mov_b32 s7, 0
	s_lshl_b64 s[6:7], s[6:7], 12
	s_add_u32 s84, s20, s6
	s_addc_u32 s85, s21, s7
	global_load_dwordx4 v[54:57], v74, s[84:85]
	global_load_dwordx4 v[58:61], v74, s[84:85] offset:1024
	global_load_dwordx4 v[62:65], v74, s[84:85] offset:2048
	global_load_dwordx4 v[66:69], v74, s[84:85] offset:3072
	s_waitcnt vmcnt(0)
	v_pk_add_f32 v[10:11], v[10:11], 1.0 op_sel_hi:[1,0]
	v_pk_add_f32 v[12:13], v[12:13], 1.0 op_sel_hi:[1,0]
	v_pk_mul_f32 v[6:7], v[6:7], v[10:11]
	v_pk_mul_f32 v[8:9], v[8:9], v[12:13]
	v_pk_add_f32 v[18:19], v[18:19], 1.0 op_sel_hi:[1,0]
	v_pk_add_f32 v[20:21], v[20:21], 1.0 op_sel_hi:[1,0]
	v_pk_mul_f32 v[14:15], v[14:15], v[18:19]
	v_pk_mul_f32 v[16:17], v[16:17], v[20:21]
	v_pk_add_f32 v[30:31], v[30:31], 1.0 op_sel_hi:[1,0]
	v_pk_add_f32 v[32:33], v[32:33], 1.0 op_sel_hi:[1,0]
	v_pk_mul_f32 v[26:27], v[26:27], v[30:31]
	v_pk_mul_f32 v[28:29], v[28:29], v[32:33]
	v_pk_add_f32 v[46:47], v[46:47], 1.0 op_sel_hi:[1,0]
	v_pk_add_f32 v[48:49], v[48:49], 1.0 op_sel_hi:[1,0]
	v_pk_mul_f32 v[38:39], v[38:39], v[46:47]
	v_pk_mul_f32 v[40:41], v[40:41], v[48:49]
	global_load_dwordx4 v[10:13], v74, s[54:55]
	global_load_dwordx4 v[18:21], v74, s[54:55] offset:1024
	global_load_dwordx4 v[30:33], v74, s[54:55] offset:2048
	global_load_dwordx4 v[46:49], v74, s[54:55] offset:3072
	s_add_u32 s86, s16, s6
	s_addc_u32 s87, s17, s7
	s_add_u32 s42, s86, 0x0
	s_addc_u32 s43, s87, 0
	global_load_dwordx4 v[116:119], v74, s[42:43]
	global_load_dwordx4 v[120:123], v74, s[42:43] offset:1024
	global_load_dwordx4 v[124:127], v74, s[42:43] offset:2048
	global_load_dwordx4 v[128:131], v74, s[42:43] offset:3072
	s_add_u32 s42, s86, 0x400000
	s_addc_u32 s43, s87, 0
	global_load_dwordx4 v[132:135], v74, s[42:43]
	global_load_dwordx4 v[136:139], v74, s[42:43] offset:1024
	global_load_dwordx4 v[140:143], v74, s[42:43] offset:2048
	global_load_dwordx4 v[144:147], v74, s[42:43] offset:3072
	s_add_u32 s42, s86, 0x800000
	s_addc_u32 s43, s87, 0
	global_load_dwordx4 v[148:151], v74, s[42:43]
	global_load_dwordx4 v[152:155], v74, s[42:43] offset:1024
	global_load_dwordx4 v[156:159], v74, s[42:43] offset:2048
	global_load_dwordx4 v[160:163], v74, s[42:43] offset:3072
	s_add_u32 s42, s86, 0xc00000
	s_addc_u32 s43, s87, 0
	global_load_dwordx4 v[164:167], v74, s[42:43]
	global_load_dwordx4 v[168:171], v74, s[42:43] offset:1024
	global_load_dwordx4 v[172:175], v74, s[42:43] offset:2048
	global_load_dwordx4 v[176:179], v74, s[42:43] offset:3072
	s_waitcnt vmcnt(0)
; __device__ __forceinline__ unsigned pk2(float lo, float hi) { const f32x2_t v = {lo, hi}; return __builtin_bit_cast(unsigned, __builtin_convertvector(v, bf16x2_t)); }
; __device__ __forceinline__ float lane_xor(float v, int lane, int o) { return __int_as_float(__builtin_amdgcn_ds_bpermute((lane ^ o) << 2, __float_as_int(v))); }
; __device__ __forceinline__ float wave_sum(float v, int lane) {
; #pragma unroll
;     for (int o = 1; o < 64; o <<= 1) v += lane_xor(v, lane, o);
;     return v;
;     ...
;             for (int ks = 0; ks < npart; ++ks) { const f32x4* pp = (const f32x4*)(part + ((size_t)ks * MC + (row - ML)) * DM);
; #pragma unroll
;                 for (int j = 0; j < 4; ++j) v[j] += pp[lane + 64 * j]; }
; #pragma unroll
;             for (int j = 0; j < 4; ++j) ((f32x4*)(srcC + (size_t)(row - ML) * DM))[lane + 64 * j] = v[j];
;         }
;         float s = 0.f;
; #pragma unroll
;         for (int j = 0; j < 4; ++j) s += (v[j].x * v[j].x + v[j].y * v[j].y) + (v[j].z * v[j].z + v[j].w * v[j].w);
;         s = wave_sum(s, lane); const float rstd = 1.0f / sqrtf(s * (1.0f / DM) + 1e-6f);
; #pragma unroll
;         for (int j = 0; j < 4; ++j) { const f32x4 y = v[j] * rstd * gs[j] + shv[j]; u32x2 w; w.x = pk2(y.x, y.y); w.y = pk2(y.z, y.w);
;             ((u32x2*)(H + (size_t)row * DM))[lane + 64 * j] = w; }
	v_pk_add_f32 v[54:55], v[54:55], v[116:117]
	v_pk_add_f32 v[56:57], v[56:57], v[118:119]
	v_pk_add_f32 v[58:59], v[58:59], v[120:121]
	v_pk_add_f32 v[60:61], v[60:61], v[122:123]
	v_pk_add_f32 v[62:63], v[62:63], v[124:125]
	v_pk_add_f32 v[64:65], v[64:65], v[126:127]
	v_pk_add_f32 v[66:67], v[66:67], v[128:129]
	v_pk_add_f32 v[68:69], v[68:69], v[130:131]
	v_pk_add_f32 v[54:55], v[54:55], v[132:133]
	v_pk_add_f32 v[56:57], v[56:57], v[134:135]
	v_pk_add_f32 v[58:59], v[58:59], v[136:137]
	v_pk_add_f32 v[60:61], v[60:61], v[138:139]
	v_pk_add_f32 v[62:63], v[62:63], v[140:141]
	v_pk_add_f32 v[64:65], v[64:65], v[142:143]
	v_pk_add_f32 v[66:67], v[66:67], v[144:145]
	v_pk_add_f32 v[68:69], v[68:69], v[146:147]
	v_pk_add_f32 v[54:55], v[54:55], v[148:149]
	v_pk_add_f32 v[56:57], v[56:57], v[150:151]
	v_pk_add_f32 v[58:59], v[58:59], v[152:153]
	v_pk_add_f32 v[60:61], v[60:61], v[154:155]
	v_pk_add_f32 v[62:63], v[62:63], v[156:157]
	v_pk_add_f32 v[64:65], v[64:65], v[158:159]
	v_pk_add_f32 v[66:67], v[66:67], v[160:161]
	v_pk_add_f32 v[68:69], v[68:69], v[162:163]
	v_pk_add_f32 v[54:55], v[54:55], v[164:165]
	v_pk_add_f32 v[56:57], v[56:57], v[166:167]
	v_pk_add_f32 v[58:59], v[58:59], v[168:169]
	v_pk_add_f32 v[60:61], v[60:61], v[170:171]
	v_pk_add_f32 v[62:63], v[62:63], v[172:173]
	v_pk_add_f32 v[64:65], v[64:65], v[174:175]
	v_pk_add_f32 v[66:67], v[66:67], v[176:177]
	v_pk_add_f32 v[68:69], v[68:69], v[178:179]
	global_store_dwordx4 v74, v[54:57], s[84:85]
	global_store_dwordx4 v74, v[58:61], s[84:85] offset:1024
	global_store_dwordx4 v74, v[62:65], s[84:85] offset:2048
	global_store_dwordx4 v74, v[66:69], s[84:85] offset:3072
	s_ashr_i32 s11, s8, 31
	s_mov_b32 s6, s8
	s_mov_b32 s7, s11
	s_lshl_b64 s[6:7], s[6:7], 11
	s_add_u32 s36, s75, s6
	s_addc_u32 s37, s76, s7
	v_pk_mul_f32 v[90:91], v[56:57], v[56:57]
	v_pk_mul_f32 v[92:93], v[54:55], v[54:55]
	v_pk_mul_f32 v[4:5], v[60:61], v[60:61]
	v_pk_mul_f32 v[88:89], v[58:59], v[58:59]
	v_pk_mov_b32 v[94:95], v[92:93], v[90:91] op_sel:[1,0]
	v_mov_b32_e32 v93, v91
	v_pk_add_f32 v[90:91], v[94:95], v[92:93]
	v_pk_mov_b32 v[92:93], v[88:89], v[4:5] op_sel:[1,0]
	v_mov_b32_e32 v89, v5
	v_pk_add_f32 v[4:5], v[92:93], v[88:89]
	v_pk_add_f32 v[90:91], v[90:91], v[90:91] op_sel_hi:[0,1]
	v_pk_add_f32 v[4:5], v[4:5], v[4:5] op_sel_hi:[0,1]
	v_mul_f32_e32 v4, v62, v62
	v_pk_fma_f32 v[88:89], v[62:63], v[62:63], v[4:5] op_sel_hi:[1,1,0]
	v_mul_f32_e32 v4, v64, v64
	v_pk_fma_f32 v[92:93], v[64:65], v[64:65], v[4:5] op_sel_hi:[1,1,0]
	v_mul_f32_e32 v88, v66, v66
	v_mul_f32_e32 v92, v67, v67
	v_mul_f32_e32 v90, v68, v68
	v_mul_f32_e32 v4, v69, v69
	v_pk_add_f32 v[88:89], v[88:89], v[92:93]
	v_pk_add_f32 v[4:5], v[90:91], v[4:5]
	v_pk_add_f32 v[4:5], v[88:89], v[4:5]
	s_nop 0
	v_add_f32_e32 v3, v4, v5
	s_nop 1
	v_add_f32_dpp v3, v3, v3 quad_perm:[1,0,3,2] row_mask:0xf bank_mask:0xf
	s_nop 1
	v_add_f32_dpp v3, v3, v3 quad_perm:[2,3,0,1] row_mask:0xf bank_mask:0xf
	s_nop 1
	v_add_f32_dpp v3, v3, v3 row_half_mirror row_mask:0xf bank_mask:0xf
	s_nop 1
	v_add_f32_dpp v3, v3, v3 row_mirror row_mask:0xf bank_mask:0xf
	s_nop 1
	v_readlane_b32 s4, v3, 0
	v_readlane_b32 s5, v3, 16
	v_readlane_b32 s6, v3, 32
	v_readlane_b32 s7, v3, 48
	s_nop 1
	v_mov_b32_e32 v4, s4
	v_add_f32_e32 v4, s5, v4
	v_mov_b32_e32 v5, s6
	v_add_f32_e32 v5, s7, v5
	v_add_f32_e32 v3, v4, v5
	v_fmamk_f32 v3, v3, 0x3a800000, v238
	v_mul_f32_e32 v4, 0x4f800000, v3
	v_cmp_gt_f32_e32 vcc, s58, v3
	s_nop 1
	v_cndmask_b32_e32 v3, v3, v4, vcc
	v_sqrt_f32_e32 v4, v3
	s_nop 0
	v_add_u32_e32 v5, -1, v4
	v_add_u32_e32 v75, 1, v4
	v_fma_f32 v88, -v5, v4, v3
	v_fma_f32 v89, -v75, v4, v3
	v_cmp_ge_f32_e64 s[4:5], 0, v88
	s_nop 1
	v_cndmask_b32_e64 v4, v4, v5, s[4:5]
	v_cmp_lt_f32_e64 s[4:5], 0, v89
	s_nop 1
	v_cndmask_b32_e64 v4, v4, v75, s[4:5]
	v_mul_f32_e32 v5, 0x37800000, v4
	v_cndmask_b32_e32 v4, v4, v5, vcc
	v_cmp_class_f32_e32 vcc, v3, v248
	s_nop 1
	v_cndmask_b32_e32 v3, v4, v3, vcc
	v_div_scale_f32 v75, s[4:5], v3, v3, 1.0
	v_rcp_f32_e32 v88, v75
	v_div_scale_f32 v89, vcc, 1.0, v3, 1.0
	v_fma_f32 v90, -v75, v88, 1.0
	v_fmac_f32_e32 v88, v90, v88
	v_mul_f32_e32 v90, v89, v88
	v_fma_f32 v91, -v75, v90, v89
	v_fmac_f32_e32 v90, v91, v88
	v_fma_f32 v75, -v75, v90, v89
	v_div_fmas_f32 v75, v75, v88, v90
	v_div_fixup_f32 v88, v75, v3, 1.0
	v_pk_mul_f32 v[54:55], v[54:55], v[88:89] op_sel_hi:[1,0]
	v_pk_mul_f32 v[56:57], v[56:57], v[88:89] op_sel_hi:[1,0]
	v_pk_fma_f32 v[54:55], v[6:7], v[54:55], v[10:11]
	v_pk_fma_f32 v[56:57], v[8:9], v[56:57], v[12:13]
	v_cvt_pk_bf16_f32 v54, v54, v55
	v_cvt_pk_bf16_f32 v55, v56, v57
	global_store_dwordx2 v86, v[54:55], s[36:37]
	v_pk_mul_f32 v[54:55], v[58:59], v[88:89] op_sel_hi:[1,0]
	v_pk_mul_f32 v[56:57], v[60:61], v[88:89] op_sel_hi:[1,0]
	v_pk_fma_f32 v[54:55], v[14:15], v[54:55], v[18:19]
	v_pk_fma_f32 v[56:57], v[16:17], v[56:57], v[20:21]
	v_cvt_pk_bf16_f32 v54, v54, v55
	v_cvt_pk_bf16_f32 v55, v56, v57
	global_store_dwordx2 v86, v[54:55], s[36:37] offset:512
	v_pk_mul_f32 v[54:55], v[62:63], v[88:89] op_sel_hi:[1,0]
	v_pk_mul_f32 v[56:57], v[64:65], v[88:89] op_sel_hi:[1,0]
	v_pk_fma_f32 v[54:55], v[26:27], v[54:55], v[30:31]
	v_pk_fma_f32 v[56:57], v[28:29], v[56:57], v[32:33]
	v_cvt_pk_bf16_f32 v54, v54, v55
	v_cvt_pk_bf16_f32 v55, v56, v57
	global_store_dwordx2 v86, v[54:55], s[36:37] offset:1024
	v_pk_mul_f32 v[54:55], v[66:67], v[88:89] op_sel_hi:[1,0]
	v_pk_mul_f32 v[56:57], v[68:69], v[88:89] op_sel_hi:[1,0]
	v_pk_fma_f32 v[56:57], v[40:41], v[56:57], v[48:49]
	v_pk_fma_f32 v[54:55], v[38:39], v[54:55], v[46:47]
	v_cvt_pk_bf16_f32 v54, v54, v55
	v_cvt_pk_bf16_f32 v55, v56, v57
	global_store_dwordx2 v86, v[54:55], s[36:37] offset:1536
	s_add_i32 s8, s8, s12
	s_cmp_lt_i32 s8, s77
	s_cbranch_scc1 .Ln4_ctxloop
